# grid barrier: waiting workgroups poll the cross-XCD generation word directly (one release hop less)
# baseline (speedup 1.0000x reference)
; __device__ __forceinline__ unsigned xb_ld(unsigned* p)              { return __hip_atomic_load(p, __ATOMIC_RELAXED, __HIP_MEMORY_SCOPE_AGENT); }
; __device__ __forceinline__ unsigned xb_add(unsigned* p, unsigned v) { return __hip_atomic_fetch_add(p, v, __ATOMIC_RELAXED, __HIP_MEMORY_SCOPE_AGENT); }
; #define XB_SPIN(cond, bar) do { unsigned _sp = 0; while (cond) { __builtin_amdgcn_s_sleep(1); \
;     if ((++_sp & 255u) == 0u) { if (xb_ld(&(bar)[XB_TMO])) break; if (_sp > XB_SPIN_CAP) { atomicAdd(&(bar)[XB_TMO], 1u); break; } } } } while (0)
; __device__ __forceinline__ void xcd_barrier(const XcdBarrier& b) {
;     ...
;         unsigned nloc = b.st[0], nx = b.st[1];
;         if (nloc == 0u) { xcd_barrier_complete(bar, b.x, nloc, nx); b.st[0] = nloc; b.st[1] = nx; }
;         const unsigned old = xb_add(&bar[XB_XSUB(b.x)], 1u);
;         const unsigned gen = old / nloc;
;         if (old + 1u == (gen + 1u) * nloc) {
;             __builtin_amdgcn_fence(__ATOMIC_RELEASE, "agent");
;             asm volatile("s_waitcnt vmcnt(0)" ::: "memory");
;             const unsigned og = xb_add(&bar[XB_TOP], 1u);
;             const unsigned tg = og / nx;
;             if (og + 1u == (tg + 1u) * nx) xb_add(&bar[XB_TOPGEN], 1u);
;             else XB_SPIN(xb_ld(&bar[XB_TOPGEN]) == tg, bar);
;             __builtin_amdgcn_fence(__ATOMIC_ACQUIRE, "agent");
;             xb_add(&bar[XB_XGEN(b.x)], 1u);
;             asm volatile("s_waitcnt vmcnt(0)" ::: "memory");
;         } else {
;             XB_SPIN(xb_ld(&bar[XB_XGEN(b.x)]) == gen, bar);
;             __builtin_amdgcn_fence(__ATOMIC_ACQUIRE, "agent");
.LBB0_162:
	s_or_b64 exec, exec, s[14:15]
	v_cvt_f32_u32_e32 v4, v2
	s_waitcnt vmcnt(0)
	v_readfirstlane_b32 s0, v3
	v_sub_u32_e32 v3, 0, v2
	v_rcp_iflag_f32_e32 v4, v4
	v_add_u32_e32 v5, s0, v1
	v_mul_f32_e32 v4, 0x4f7ffffe, v4
	v_cvt_u32_f32_e32 v4, v4
	v_mul_lo_u32 v1, v3, v4
	v_mul_hi_u32 v1, v4, v1
	v_add_u32_e32 v1, v4, v1
	v_mul_hi_u32 v1, v5, v1
	v_mul_lo_u32 v3, v1, v2
	v_sub_u32_e32 v3, v5, v3
	v_add_u32_e32 v4, 1, v1
	v_cmp_ge_u32_e32 vcc, v3, v2
	s_nop 1
	v_cndmask_b32_e32 v1, v1, v4, vcc
	v_sub_u32_e32 v4, v3, v2
	v_cndmask_b32_e32 v3, v3, v4, vcc
	v_add_u32_e32 v4, 1, v1
	v_cmp_ge_u32_e32 vcc, v3, v2
	v_add_u32_e32 v3, 1, v5
	s_nop 0
	v_cndmask_b32_e32 v1, v1, v4, vcc
	v_mul_lo_u32 v4, v2, v1
	v_add_u32_e32 v2, v4, v2
	v_cmp_ne_u32_e32 vcc, v3, v2
	s_and_saveexec_b64 s[0:1], vcc
	s_xor_b64 s[12:13], exec, s[0:1]
	s_cbranch_execz .LBB0_176
	s_waitcnt lgkmcnt(0)
	v_mov_b32_e32 v0, 0x3100
	global_load_dword v0, v0, s[6:7] offset:1024 sc1
	s_add_u32 s16, s6, 0x3500
	s_addc_u32 s17, s7, 0
	s_waitcnt vmcnt(0)
	v_cmp_eq_u32_e32 vcc, v0, v1
	s_and_saveexec_b64 s[14:15], vcc
	s_cbranch_execz .LBB0_175
	s_mov_b32 s10, 1
	s_mov_b64 s[18:19], 0
	v_mov_b32_e32 v0, 0
	s_branch .LBB0_166

; __device__ __forceinline__ unsigned xb_ld(unsigned* p)              { return __hip_atomic_load(p, __ATOMIC_RELAXED, __HIP_MEMORY_SCOPE_AGENT); }
; __device__ __forceinline__ unsigned xb_add(unsigned* p, unsigned v) { return __hip_atomic_fetch_add(p, v, __ATOMIC_RELAXED, __HIP_MEMORY_SCOPE_AGENT); }
; #define XB_SPIN(cond, bar) do { unsigned _sp = 0; while (cond) { __builtin_amdgcn_s_sleep(1); \
;     if ((++_sp & 255u) == 0u) { if (xb_ld(&(bar)[XB_TMO])) break; if (_sp > XB_SPIN_CAP) { atomicAdd(&(bar)[XB_TMO], 1u); break; } } } } while (0)
; __device__ __forceinline__ void xcd_barrier(const XcdBarrier& b) {
;     ...
;         unsigned nloc = b.st[0], nx = b.st[1];
;         if (nloc == 0u) { xcd_barrier_complete(bar, b.x, nloc, nx); b.st[0] = nloc; b.st[1] = nx; }
;         const unsigned old = xb_add(&bar[XB_XSUB(b.x)], 1u);
;         const unsigned gen = old / nloc;
;         if (old + 1u == (gen + 1u) * nloc) {
;             __builtin_amdgcn_fence(__ATOMIC_RELEASE, "agent");
;             asm volatile("s_waitcnt vmcnt(0)" ::: "memory");
;             const unsigned og = xb_add(&bar[XB_TOP], 1u);
;             const unsigned tg = og / nx;
;             if (og + 1u == (tg + 1u) * nx) xb_add(&bar[XB_TOPGEN], 1u);
;             else XB_SPIN(xb_ld(&bar[XB_TOPGEN]) == tg, bar);
;             __builtin_amdgcn_fence(__ATOMIC_ACQUIRE, "agent");
;             xb_add(&bar[XB_XGEN(b.x)], 1u);
;             asm volatile("s_waitcnt vmcnt(0)" ::: "memory");
;         } else {
;             XB_SPIN(xb_ld(&bar[XB_XGEN(b.x)]) == gen, bar);
;             __builtin_amdgcn_fence(__ATOMIC_ACQUIRE, "agent");
.LBB0_243:
	s_or_b64 exec, exec, s[16:17]
	v_cvt_f32_u32_e32 v4, v2
	s_waitcnt vmcnt(0)
	v_readfirstlane_b32 s0, v3
	v_sub_u32_e32 v3, 0, v2
	v_rcp_iflag_f32_e32 v4, v4
	v_add_u32_e32 v5, s0, v1
	v_mul_f32_e32 v4, 0x4f7ffffe, v4
	v_cvt_u32_f32_e32 v4, v4
	v_mul_lo_u32 v1, v3, v4
	v_mul_hi_u32 v1, v4, v1
	v_add_u32_e32 v1, v4, v1
	v_mul_hi_u32 v1, v5, v1
	v_mul_lo_u32 v3, v1, v2
	v_sub_u32_e32 v3, v5, v3
	v_add_u32_e32 v4, 1, v1
	v_cmp_ge_u32_e32 vcc, v3, v2
	s_nop 1
	v_cndmask_b32_e32 v1, v1, v4, vcc
	v_sub_u32_e32 v4, v3, v2
	v_cndmask_b32_e32 v3, v3, v4, vcc
	v_add_u32_e32 v4, 1, v1
	v_cmp_ge_u32_e32 vcc, v3, v2
	v_add_u32_e32 v3, 1, v5
	s_nop 0
	v_cndmask_b32_e32 v1, v1, v4, vcc
	v_mul_lo_u32 v4, v2, v1
	v_add_u32_e32 v2, v4, v2
	v_cmp_ne_u32_e32 vcc, v3, v2
	s_and_saveexec_b64 s[0:1], vcc
	s_xor_b64 s[14:15], exec, s[0:1]
	s_cbranch_execz .LBB0_257
	s_waitcnt lgkmcnt(0)
	v_mov_b32_e32 v0, 0x3100
	global_load_dword v0, v0, s[8:9] offset:1024 sc1
	s_add_u32 s18, s8, 0x3500
	s_addc_u32 s19, s9, 0
	s_waitcnt vmcnt(0)
	v_cmp_eq_u32_e32 vcc, v0, v1
	s_and_saveexec_b64 s[16:17], vcc
	s_cbranch_execz .LBB0_256
	s_mov_b32 s10, 1
	s_mov_b64 s[20:21], 0
	v_mov_b32_e32 v0, 0
	s_branch .LBB0_247

; __device__ __forceinline__ unsigned xb_ld(unsigned* p)              { return __hip_atomic_load(p, __ATOMIC_RELAXED, __HIP_MEMORY_SCOPE_AGENT); }
; __device__ __forceinline__ unsigned xb_add(unsigned* p, unsigned v) { return __hip_atomic_fetch_add(p, v, __ATOMIC_RELAXED, __HIP_MEMORY_SCOPE_AGENT); }
; #define XB_SPIN(cond, bar) do { unsigned _sp = 0; while (cond) { __builtin_amdgcn_s_sleep(1); \
;     if ((++_sp & 255u) == 0u) { if (xb_ld(&(bar)[XB_TMO])) break; if (_sp > XB_SPIN_CAP) { atomicAdd(&(bar)[XB_TMO], 1u); break; } } } } while (0)
; __device__ __forceinline__ void xcd_barrier(const XcdBarrier& b) {
;     ...
;         unsigned nloc = b.st[0], nx = b.st[1];
;         if (nloc == 0u) { xcd_barrier_complete(bar, b.x, nloc, nx); b.st[0] = nloc; b.st[1] = nx; }
;         const unsigned old = xb_add(&bar[XB_XSUB(b.x)], 1u);
;         const unsigned gen = old / nloc;
;         if (old + 1u == (gen + 1u) * nloc) {
;             __builtin_amdgcn_fence(__ATOMIC_RELEASE, "agent");
;             asm volatile("s_waitcnt vmcnt(0)" ::: "memory");
;             const unsigned og = xb_add(&bar[XB_TOP], 1u);
;             const unsigned tg = og / nx;
;             if (og + 1u == (tg + 1u) * nx) xb_add(&bar[XB_TOPGEN], 1u);
;             else XB_SPIN(xb_ld(&bar[XB_TOPGEN]) == tg, bar);
;             __builtin_amdgcn_fence(__ATOMIC_ACQUIRE, "agent");
;             xb_add(&bar[XB_XGEN(b.x)], 1u);
;             asm volatile("s_waitcnt vmcnt(0)" ::: "memory");
;         } else {
;             XB_SPIN(xb_ld(&bar[XB_XGEN(b.x)]) == gen, bar);
;             __builtin_amdgcn_fence(__ATOMIC_ACQUIRE, "agent");
.LBB0_440:
	s_or_b64 exec, exec, s[16:17]
	v_cvt_f32_u32_e32 v4, v2
	s_waitcnt vmcnt(0)
	v_readfirstlane_b32 s0, v3
	v_sub_u32_e32 v3, 0, v2
	v_rcp_iflag_f32_e32 v4, v4
	v_add_u32_e32 v5, s0, v1
	v_mul_f32_e32 v4, 0x4f7ffffe, v4
	v_cvt_u32_f32_e32 v4, v4
	v_mul_lo_u32 v1, v3, v4
	v_mul_hi_u32 v1, v4, v1
	v_add_u32_e32 v1, v4, v1
	v_mul_hi_u32 v1, v5, v1
	v_mul_lo_u32 v3, v1, v2
	v_sub_u32_e32 v3, v5, v3
	v_add_u32_e32 v4, 1, v1
	v_cmp_ge_u32_e32 vcc, v3, v2
	s_nop 1
	v_cndmask_b32_e32 v1, v1, v4, vcc
	v_sub_u32_e32 v4, v3, v2
	v_cndmask_b32_e32 v3, v3, v4, vcc
	v_add_u32_e32 v4, 1, v1
	v_cmp_ge_u32_e32 vcc, v3, v2
	v_add_u32_e32 v3, 1, v5
	s_nop 0
	v_cndmask_b32_e32 v1, v1, v4, vcc
	v_mul_lo_u32 v4, v2, v1
	v_add_u32_e32 v2, v4, v2
	v_cmp_ne_u32_e32 vcc, v3, v2
	s_and_saveexec_b64 s[0:1], vcc
	s_xor_b64 s[14:15], exec, s[0:1]
	s_cbranch_execz .LBB0_454
	s_waitcnt lgkmcnt(0)
	v_mov_b32_e32 v0, 0x3100
	global_load_dword v0, v0, s[10:11] offset:1024 sc1
	s_add_u32 s18, s10, 0x3500
	s_addc_u32 s19, s11, 0
	s_waitcnt vmcnt(0)
	v_cmp_eq_u32_e32 vcc, v0, v1
	s_and_saveexec_b64 s[16:17], vcc
	s_cbranch_execz .LBB0_453
	s_mov_b32 s30, 1
	s_mov_b64 s[20:21], 0
	v_mov_b32_e32 v0, 0
	s_branch .LBB0_444

; __device__ __forceinline__ unsigned xb_ld(unsigned* p)              { return __hip_atomic_load(p, __ATOMIC_RELAXED, __HIP_MEMORY_SCOPE_AGENT); }
; __device__ __forceinline__ unsigned xb_add(unsigned* p, unsigned v) { return __hip_atomic_fetch_add(p, v, __ATOMIC_RELAXED, __HIP_MEMORY_SCOPE_AGENT); }
; #define XB_SPIN(cond, bar) do { unsigned _sp = 0; while (cond) { __builtin_amdgcn_s_sleep(1); \
;     if ((++_sp & 255u) == 0u) { if (xb_ld(&(bar)[XB_TMO])) break; if (_sp > XB_SPIN_CAP) { atomicAdd(&(bar)[XB_TMO], 1u); break; } } } } while (0)
; __device__ __forceinline__ void xcd_barrier(const XcdBarrier& b) {
;     ...
;         unsigned nloc = b.st[0], nx = b.st[1];
;         if (nloc == 0u) { xcd_barrier_complete(bar, b.x, nloc, nx); b.st[0] = nloc; b.st[1] = nx; }
;         const unsigned old = xb_add(&bar[XB_XSUB(b.x)], 1u);
;         const unsigned gen = old / nloc;
;         if (old + 1u == (gen + 1u) * nloc) {
;             __builtin_amdgcn_fence(__ATOMIC_RELEASE, "agent");
;             asm volatile("s_waitcnt vmcnt(0)" ::: "memory");
;             const unsigned og = xb_add(&bar[XB_TOP], 1u);
;             const unsigned tg = og / nx;
;             if (og + 1u == (tg + 1u) * nx) xb_add(&bar[XB_TOPGEN], 1u);
;             else XB_SPIN(xb_ld(&bar[XB_TOPGEN]) == tg, bar);
;             __builtin_amdgcn_fence(__ATOMIC_ACQUIRE, "agent");
;             xb_add(&bar[XB_XGEN(b.x)], 1u);
;             asm volatile("s_waitcnt vmcnt(0)" ::: "memory");
;         } else {
;             XB_SPIN(xb_ld(&bar[XB_XGEN(b.x)]) == gen, bar);
;             __builtin_amdgcn_fence(__ATOMIC_ACQUIRE, "agent");
.LBB0_622:
	s_or_b64 exec, exec, s[18:19]
	v_cvt_f32_u32_e32 v4, v2
	s_waitcnt vmcnt(0)
	v_readfirstlane_b32 s0, v3
	v_sub_u32_e32 v3, 0, v2
	v_rcp_iflag_f32_e32 v4, v4
	v_add_u32_e32 v5, s0, v1
	v_mul_f32_e32 v4, 0x4f7ffffe, v4
	v_cvt_u32_f32_e32 v4, v4
	v_mul_lo_u32 v1, v3, v4
	v_mul_hi_u32 v1, v4, v1
	v_add_u32_e32 v1, v4, v1
	v_mul_hi_u32 v1, v5, v1
	v_mul_lo_u32 v3, v1, v2
	v_sub_u32_e32 v3, v5, v3
	v_add_u32_e32 v4, 1, v1
	v_cmp_ge_u32_e32 vcc, v3, v2
	s_nop 1
	v_cndmask_b32_e32 v1, v1, v4, vcc
	v_sub_u32_e32 v4, v3, v2
	v_cndmask_b32_e32 v3, v3, v4, vcc
	v_add_u32_e32 v4, 1, v1
	v_cmp_ge_u32_e32 vcc, v3, v2
	v_add_u32_e32 v3, 1, v5
	s_nop 0
	v_cndmask_b32_e32 v1, v1, v4, vcc
	v_mul_lo_u32 v4, v2, v1
	v_add_u32_e32 v2, v4, v2
	v_cmp_ne_u32_e32 vcc, v3, v2
	s_and_saveexec_b64 s[0:1], vcc
	s_xor_b64 s[16:17], exec, s[0:1]
	s_cbranch_execz .LBB0_636
	s_waitcnt lgkmcnt(0)
	v_mov_b32_e32 v0, 0x3100
	global_load_dword v0, v0, s[12:13] offset:1024 sc1
	s_add_u32 s20, s12, 0x3500
	s_addc_u32 s21, s13, 0
	s_waitcnt vmcnt(0)
	v_cmp_eq_u32_e32 vcc, v0, v1
	s_and_saveexec_b64 s[18:19], vcc
	s_cbranch_execz .LBB0_635
	s_mov_b32 s34, 1
	s_mov_b64 s[22:23], 0
	v_mov_b32_e32 v0, 0
	s_branch .LBB0_626

; __device__ __forceinline__ unsigned xb_ld(unsigned* p)              { return __hip_atomic_load(p, __ATOMIC_RELAXED, __HIP_MEMORY_SCOPE_AGENT); }
; __device__ __forceinline__ unsigned xb_add(unsigned* p, unsigned v) { return __hip_atomic_fetch_add(p, v, __ATOMIC_RELAXED, __HIP_MEMORY_SCOPE_AGENT); }
; #define XB_SPIN(cond, bar) do { unsigned _sp = 0; while (cond) { __builtin_amdgcn_s_sleep(1); \
;     if ((++_sp & 255u) == 0u) { if (xb_ld(&(bar)[XB_TMO])) break; if (_sp > XB_SPIN_CAP) { atomicAdd(&(bar)[XB_TMO], 1u); break; } } } } while (0)
; __device__ __forceinline__ void xcd_barrier(const XcdBarrier& b) {
;     ...
;         unsigned nloc = b.st[0], nx = b.st[1];
;         if (nloc == 0u) { xcd_barrier_complete(bar, b.x, nloc, nx); b.st[0] = nloc; b.st[1] = nx; }
;         const unsigned old = xb_add(&bar[XB_XSUB(b.x)], 1u);
;         const unsigned gen = old / nloc;
;         if (old + 1u == (gen + 1u) * nloc) {
;             __builtin_amdgcn_fence(__ATOMIC_RELEASE, "agent");
;             asm volatile("s_waitcnt vmcnt(0)" ::: "memory");
;             const unsigned og = xb_add(&bar[XB_TOP], 1u);
;             const unsigned tg = og / nx;
;             if (og + 1u == (tg + 1u) * nx) xb_add(&bar[XB_TOPGEN], 1u);
;             else XB_SPIN(xb_ld(&bar[XB_TOPGEN]) == tg, bar);
;             __builtin_amdgcn_fence(__ATOMIC_ACQUIRE, "agent");
;             xb_add(&bar[XB_XGEN(b.x)], 1u);
;             asm volatile("s_waitcnt vmcnt(0)" ::: "memory");
;         } else {
;             XB_SPIN(xb_ld(&bar[XB_XGEN(b.x)]) == gen, bar);
;             __builtin_amdgcn_fence(__ATOMIC_ACQUIRE, "agent");
.LBB0_1238:
	s_or_b64 exec, exec, s[14:15]
	v_cvt_f32_u32_e32 v4, v2
	s_waitcnt vmcnt(0)
	v_readfirstlane_b32 s0, v3
	v_sub_u32_e32 v3, 0, v2
	v_rcp_iflag_f32_e32 v4, v4
	v_add_u32_e32 v5, s0, v1
	v_mul_f32_e32 v4, 0x4f7ffffe, v4
	v_cvt_u32_f32_e32 v4, v4
	v_mul_lo_u32 v1, v3, v4
	v_mul_hi_u32 v1, v4, v1
	v_add_u32_e32 v1, v4, v1
	v_mul_hi_u32 v1, v5, v1
	v_mul_lo_u32 v3, v1, v2
	v_sub_u32_e32 v3, v5, v3
	v_add_u32_e32 v4, 1, v1
	v_cmp_ge_u32_e32 vcc, v3, v2
	s_nop 1
	v_cndmask_b32_e32 v1, v1, v4, vcc
	v_sub_u32_e32 v4, v3, v2
	v_cndmask_b32_e32 v3, v3, v4, vcc
	v_add_u32_e32 v4, 1, v1
	v_cmp_ge_u32_e32 vcc, v3, v2
	v_add_u32_e32 v3, 1, v5
	s_nop 0
	v_cndmask_b32_e32 v1, v1, v4, vcc
	v_mul_lo_u32 v4, v2, v1
	v_add_u32_e32 v2, v4, v2
	v_cmp_ne_u32_e32 vcc, v3, v2
	s_and_saveexec_b64 s[0:1], vcc
	s_xor_b64 s[12:13], exec, s[0:1]
	s_cbranch_execz .LBB0_1252
	s_waitcnt lgkmcnt(0)
	v_mov_b32_e32 v0, 0x3100
	global_load_dword v0, v0, s[8:9] offset:1024 sc1
	s_add_u32 s16, s8, 0x3500
	s_addc_u32 s17, s9, 0
	s_waitcnt vmcnt(0)
	v_cmp_eq_u32_e32 vcc, v0, v1
	s_and_saveexec_b64 s[14:15], vcc
	s_cbranch_execz .LBB0_1251
	s_mov_b32 s28, 1
	s_mov_b64 s[18:19], 0
	v_mov_b32_e32 v0, 0
	s_branch .LBB0_1242
